# GLA chunk loop stage B: output-tile fragment reads issued up front into idle registers, the row-tile MFMA chains interleaved pairwise (on the 12472 split)
# baseline (speedup 1.0000x reference)
; #define LAS __attribute__((address_space(3)))
; __device__ __forceinline__ s16x4_t tr_read(LAS const unsigned char* p) { return __builtin_bit_cast(s16x4_t, __builtin_amdgcn_ds_read_tr16_b64_v4i16((LAS s16x4_t*)p)); }
; __device__ __forceinline__ void p2b_gla_main(Frame& F) {
;     ...
;             bf16x8_t vf[2];
; #pragma unroll
;             for (int s = 0; s < 2; ++s) { const LAS unsigned char* vp = lds + L_V + (32 * s + 8 * g + q4) * VST + (16 * cw + 4 * p4) * 2; vf[s] = cat8(tr_read(vp), tr_read(vp + 4 * VST)); }
;             bf16x8_t sb[4];
; #pragma unroll
;             for (int s = 0; s < 4; ++s) { v4u t; t.x = cvtpk(S[2 * s][0], S[2 * s][1]); t.y = cvtpk(S[2 * s][2], S[2 * s][3]); t.z = cvtpk(S[2 * s + 1][0], S[2 * s + 1][1]); t.w = cvtpk(S[2 * s + 1][2], S[2 * s + 1][3]); sb[s] = __builtin_bit_cast(bf16x8_t, t); }
;             float gs[8];
; #pragma unroll
;             for (int j = 0; j < 4; ++j) { const unsigned wj = cgr[j]; const float x0 = bflo(wj), x1 = bfhi(wj);
;                 const unsigned wb_ = (j < 2) ? cgb.x : cgb.y; const int sh = 16 * (j & 1);
;                 const float b0 = ((float)((wb_ >> sh) & 0xffu) - 128.f) * 0.03125f, b1 = ((float)((wb_ >> (sh + 8)) & 0xffu) - 128.f) * 0.03125f;
;                 gs[2 * j] = gwv[2 * j] * x0 * __builtin_amdgcn_rcpf((1.0f + __builtin_amdgcn_exp2f(-1.4426950408889634f * x0)) * (1.0f + __builtin_amdgcn_exp2f(-1.4426950408889634f * b0)));
;                 gs[2 * j + 1] = gwv[2 * j + 1] * x1 * __builtin_amdgcn_rcpf((1.0f + __builtin_amdgcn_exp2f(-1.4426950408889634f * x1)) * (1.0f + __builtin_amdgcn_exp2f(-1.4426950408889634f * b1))); }
; #pragma unroll
;             for (int it = 0; it < 4; ++it) {
;                 f32x4 oa = {0.f, 0.f, 0.f, 0.f};
;                 { const bf16x8_t a = *(const LAS bf16x8_t*)(lds + L_ATT + (16 * it + c16) * AST + (32 * kh + 8 * g) * 2); oa = MFMA16(a, kh ? vf[1] : vf[0], oa); }
;                 const LAS unsigned char* qp = lds + L_QD + (16 * it + c16) * QST + (128 * kh) * 2 + g * 16;
; #pragma unroll
;                 for (int s = 0; s < 4; ++s) oa = MFMA16(*(const LAS bf16x8_t*)(qp + s * 64), sb[s], oa);
; #pragma unroll
;                 for (int r = 0; r < 4; ++r) *(LAS float*)(lds + L_OP + kh * 64 * OST + (16 * it + 4 * g + r) * OST + (16 * cw + c16) * 4) = oa[r];
;                 if (c + 1 < SEQ / GCHUNK) GLA_LOAD_QK(c + 1, it);
;             }
.LBB0_549:
	s_or_b64 exec, exec, s[28:29]
	ds_read_b64_tr_b16 v[62:63], v181
	ds_read_b64_tr_b16 v[64:65], v181 offset:576
	ds_read_b64_tr_b16 v[90:91], v181 offset:4608
	ds_read_b64_tr_b16 v[92:93], v181 offset:5184
	ds_read_b128 v[66:69], v182
	ds_read_b128 v[86:89], v182 offset:2304
	ds_read_b128 v[190:193], v184
	ds_read_b128 v[194:197], v184 offset:8448
	ds_read_b128 v[198:201], v184 offset:64
	ds_read_b128 v[202:205], v184 offset:8512
	ds_read_b128 v[206:209], v184 offset:128
	ds_read_b128 v[210:213], v184 offset:8576
	ds_read_b128 v[214:217], v184 offset:192
	ds_read_b128 v[218:221], v184 offset:8640
	v_cvt_pk_bf16_f32 v58, v42, v43
	v_cvt_pk_bf16_f32 v59, v44, v45
	v_cvt_pk_bf16_f32 v60, v46, v47
	v_cvt_pk_bf16_f32 v61, v48, v49
	v_cvt_pk_bf16_f32 v70, v34, v35
	v_cvt_pk_bf16_f32 v71, v36, v37
	v_cvt_pk_bf16_f32 v72, v26, v27
	v_cvt_pk_bf16_f32 v73, v28, v29
	v_cvt_pk_bf16_f32 v78, v30, v31
	v_cvt_pk_bf16_f32 v79, v32, v33
	v_cvt_pk_bf16_f32 v80, v38, v39
	v_cvt_pk_bf16_f32 v81, v40, v41
	v_cvt_pk_bf16_f32 v82, v18, v19
	v_cvt_pk_bf16_f32 v83, v20, v21
	v_cvt_pk_bf16_f32 v84, v22, v23
	v_cvt_pk_bf16_f32 v85, v24, v25
	v_add_u32_e32 v188, 0x1000, v185
	v_add_u32_e32 v189, 0x1200, v185
	v_add_u32_e32 v135, 0x2000, v185
	v_add_u32_e32 v137, 0x2400, v185
	v_add_u32_e32 v131, 0x3200, v185
	v_add_u32_e32 v133, 0x3400, v185
	s_waitcnt lgkmcnt(10)
	v_cndmask_b32_e64 v77, v93, v65, s[6:7]
	v_cndmask_b32_e64 v76, v92, v64, s[6:7]
	v_cndmask_b32_e64 v75, v91, v63, s[6:7]
	v_cndmask_b32_e64 v74, v90, v62, s[6:7]
	s_waitcnt lgkmcnt(9)
	s_nop 1
	v_mfma_f32_16x16x32_bf16 v[66:69], v[66:69], v[74:77], 0
	s_waitcnt lgkmcnt(8)
	v_mfma_f32_16x16x32_bf16 v[86:89], v[86:89], v[74:77], 0
	ds_read_b128 v[242:245], v182 offset:4608
	ds_read_b128 v[238:241], v182 offset:6912
	s_waitcnt lgkmcnt(9)
	v_mfma_f32_16x16x32_bf16 v[66:69], v[190:193], v[58:61], v[66:69]
	s_waitcnt lgkmcnt(8)
	v_mfma_f32_16x16x32_bf16 v[86:89], v[194:197], v[58:61], v[86:89]
	ds_read_b128 v[222:225], v184 offset:16896
	ds_read_b128 v[226:229], v184 offset:25344
	s_waitcnt lgkmcnt(9)
	v_mfma_f32_16x16x32_bf16 v[66:69], v[198:201], v[70:73], v[66:69]
	s_waitcnt lgkmcnt(8)
	v_mfma_f32_16x16x32_bf16 v[86:89], v[202:205], v[70:73], v[86:89]
	ds_read_b128 v[230:233], v184 offset:16960
	ds_read_b128 v[234:237], v184 offset:25408
	s_waitcnt lgkmcnt(9)
	v_mfma_f32_16x16x32_bf16 v[66:69], v[206:209], v[78:81], v[66:69]
	s_waitcnt lgkmcnt(8)
	v_mfma_f32_16x16x32_bf16 v[86:89], v[210:213], v[78:81], v[86:89]
	ds_read_b128 v[190:193], v184 offset:17024
	ds_read_b128 v[194:197], v184 offset:25472
	s_waitcnt lgkmcnt(9)
	v_mfma_f32_16x16x32_bf16 v[66:69], v[214:217], v[82:85], v[66:69]
	s_waitcnt lgkmcnt(8)
	v_mfma_f32_16x16x32_bf16 v[86:89], v[218:221], v[82:85], v[86:89]
	ds_read_b128 v[198:201], v184 offset:17088
	ds_read_b128 v[202:205], v184 offset:25536
	s_waitcnt lgkmcnt(9)
	v_mfma_f32_16x16x32_bf16 v[242:245], v[242:245], v[74:77], 0
	s_waitcnt lgkmcnt(8)
	v_mfma_f32_16x16x32_bf16 v[238:241], v[238:241], v[74:77], 0
	s_waitcnt lgkmcnt(7)
	v_mfma_f32_16x16x32_bf16 v[242:245], v[222:225], v[58:61], v[242:245]
	s_waitcnt lgkmcnt(6)
	v_mfma_f32_16x16x32_bf16 v[238:241], v[226:229], v[58:61], v[238:241]
	ds_write2_b32 v185, v66, v67 offset1:68
	ds_write2_b32 v185, v68, v69 offset0:136 offset1:204
	ds_write2_b32 v188, v86, v87 offset0:64 offset1:132
	ds_write2_b32 v189, v88, v89 offset0:72 offset1:140
	s_waitcnt lgkmcnt(9)
	v_mfma_f32_16x16x32_bf16 v[242:245], v[230:233], v[70:73], v[242:245]
	s_waitcnt lgkmcnt(8)
	v_mfma_f32_16x16x32_bf16 v[238:241], v[234:237], v[70:73], v[238:241]
	s_waitcnt lgkmcnt(7)
	v_mfma_f32_16x16x32_bf16 v[242:245], v[190:193], v[78:81], v[242:245]
	s_waitcnt lgkmcnt(6)
	v_mfma_f32_16x16x32_bf16 v[238:241], v[194:197], v[78:81], v[238:241]
	s_waitcnt lgkmcnt(5)
	v_mfma_f32_16x16x32_bf16 v[242:245], v[198:201], v[82:85], v[242:245]
	s_waitcnt lgkmcnt(4)
	v_mfma_f32_16x16x32_bf16 v[238:241], v[202:205], v[82:85], v[238:241]
	v_lshl_add_u64 v[190:191], s[56:57], 0, v[146:147]
	v_lshl_add_u64 v[86:87], s[56:57], 0, v[148:149]
	v_add_u32_e32 v214, s34, v99
	v_add_co_u32_e32 v194, vcc, s70, v86
	v_addc_co_u32_e32 v195, vcc, 0, v87, vcc
	s_nop 7
	ds_write2_b32 v135, v242, v243 offset0:128 offset1:196
	ds_write2_b32 v137, v244, v245 offset0:8 offset1:76
	ds_write2_b32 v131, v238, v239 offset0:64 offset1:132
	ds_write2_b32 v133, v240, v241 offset0:72 offset1:140
	ds_read_b128 v[58:61], v163 offset:33792
	ds_read_b128 v[66:69], v164 offset:33792
	v_lshl_add_u64 v[82:83], s[56:57], 0, v[152:153]
	ds_read_b128 v[70:73], v163 offset:33856
	ds_read_b128 v[74:77], v165 offset:33792
	s_waitcnt lgkmcnt(3)
	v_mfma_f32_16x16x32_bf16 v[42:45], v[58:61], v[62:65], v[42:45]
	v_add_co_u32_e32 v202, vcc, s70, v82
	s_waitcnt lgkmcnt(2)
	v_mfma_f32_16x16x32_bf16 v[58:61], v[66:69], v[62:65], v[46:49]
	s_nop 2
	ds_read_b128 v[46:49], v166 offset:33792
	ds_read_b128 v[66:69], v165 offset:33856
	ds_read_b128 v[78:81], v167 offset:33792
	v_addc_co_u32_e32 v203, vcc, 0, v83, vcc
	s_waitcnt lgkmcnt(2)
	v_mfma_f32_16x16x32_bf16 v[82:85], v[46:49], v[62:65], v[26:29]
	v_add_co_u32_e32 v46, vcc, s71, v86
	s_nop 1
	v_addc_co_u32_e32 v47, vcc, 0, v87, vcc
	v_add_co_u32_e32 v218, vcc, s70, v190
	v_mfma_f32_16x16x32_bf16 v[34:37], v[74:77], v[62:65], v[34:37]
	s_nop 0
	v_addc_co_u32_e32 v219, vcc, 0, v191, vcc
	ds_read_b128 v[74:77], v168 offset:33792
	ds_read_b128 v[86:89], v167 offset:33856
	ds_read_b128 v[26:29], v164 offset:33856
	global_load_dwordx4 v[190:193], v[194:195], off offset:1024
	s_nop 0
	global_load_dwordx4 v[194:197], v[194:195], off offset:3072
	s_nop 0
	global_load_dwordx4 v[198:201], v[202:203], off offset:1024
	s_nop 0
	global_load_dwordx4 v[202:205], v[202:203], off offset:3072
	s_nop 0
	global_load_dwordx4 v[206:209], v[46:47], off offset:1024
	global_load_dwordx4 v[210:213], v[46:47], off offset:3072
	ds_read_b128 v[46:49], v214
	global_load_dwordx4 v[214:217], v[218:219], off offset:1024
	s_nop 0
	global_load_dwordx4 v[218:221], v[218:219], off offset:3072
	s_waitcnt lgkmcnt(4)
; #define LAS __attribute__((address_space(3)))
; #define MFMA16(a, b, c) __builtin_amdgcn_mfma_f32_16x16x32_bf16((a), (b), (c), 0, 0, 0)
; __device__ __forceinline__ void p2b_gla_main(Frame& F) {
;     ...
; #pragma unroll
;             for (int t = 0; t < 8; ++t) {
;                 const LAS unsigned char* kp = lds + L_KT + (128 * kh + 16 * t + c16) * KST + g * 16;
; #pragma unroll
;                 for (int s = 0; s < 2; ++s) S[t] = MFMA16(*(const LAS bf16x8_t*)(kp + s * 64), vf[s], S[t]);
;                 const f32x4 dc = *(const LAS f32x4*)(lds + L_DEC + (128 * kh + 16 * t + 4 * g) * 4);
;                 S[t] = S[t] * dc;
;             }
	v_mfma_f32_16x16x32_bf16 v[30:33], v[78:81], v[62:65], v[30:33]
	s_waitcnt lgkmcnt(3)
	v_mfma_f32_16x16x32_bf16 v[78:81], v[74:77], v[62:65], v[38:41]
	s_nop 2
	ds_read_b128 v[38:41], v166 offset:33856
	s_waitcnt lgkmcnt(2)
	v_mfma_f32_16x16x32_bf16 v[74:77], v[26:29], v[90:93], v[58:61]
	v_add_u32_e32 v26, s36, v99
	ds_read_b128 v[26:29], v26
	v_mfma_f32_16x16x32_bf16 v[34:37], v[66:69], v[90:93], v[34:37]
	ds_read_b128 v[58:61], v168 offset:33856
	ds_read_b128 v[66:69], v169 offset:33792
	v_mfma_f32_16x16x32_bf16 v[42:45], v[70:73], v[90:93], v[42:45]
	s_waitcnt lgkmcnt(3)
	v_mfma_f32_16x16x32_bf16 v[70:73], v[38:41], v[90:93], v[82:85]
	v_add_u32_e32 v38, s38, v99
	ds_read_b128 v[38:41], v38
	ds_read_b128 v[222:225], v169 offset:33856
	s_waitcnt lgkmcnt(3)
	v_mfma_f32_16x16x32_bf16 v[58:61], v[58:61], v[90:93], v[78:81]
	s_nop 2
	v_add_u32_e32 v78, s1, v99
	v_mfma_f32_16x16x32_bf16 v[30:33], v[86:89], v[90:93], v[30:33]
	ds_read_b128 v[86:89], v78
	ds_read_b128 v[226:229], v170 offset:33792
	s_waitcnt lgkmcnt(4)
	v_mfma_f32_16x16x32_bf16 v[18:21], v[66:69], v[62:65], v[18:21]
	v_add_u32_e32 v66, s35, v99
	ds_read_b128 v[82:85], v66
	ds_read_b128 v[230:233], v170 offset:33856
	v_add_u32_e32 v66, s37, v99
	s_waitcnt lgkmcnt(2)
	v_mfma_f32_16x16x32_bf16 v[62:65], v[226:229], v[62:65], v[22:25]
	ds_read_b128 v[78:81], v66
	s_nop 1
	v_add_u32_e32 v22, s40, v99
	ds_read_b128 v[22:25], v22
	v_add_u32_e32 v66, s39, v99
	ds_read_b128 v[66:69], v66
	v_mfma_f32_16x16x32_bf16 v[18:21], v[222:225], v[90:93], v[18:21]
	s_waitcnt lgkmcnt(0)
	s_barrier
; #define LAS __attribute__((address_space(3)))
;     __device__ __forceinline__ float* SSQG() const { return (float*)(ws + WS_SSQG); }
; #define GLA_TICK(sec) do { if (blockIdx.x == 0 && F.wave == 0) { const unsigned tn_ = (unsigned)__builtin_amdgcn_s_memrealtime(); if ((sec) == PROBE_KIND) F.MISC[60] += tn_ - F.MISC[61]; F.MISC[61] = tn_; } } while (0)
; #define GLA_TICK(sec) do { } while (0)
; __device__ __forceinline__ void p2b_gla_main(Frame& F) {
;     ...
;             float gs[8];
; #pragma unroll
;             for (int j = 0; j < 4; ++j) { const unsigned wj = cgr[j]; const float x0 = bflo(wj), x1 = bfhi(wj);
;                 const unsigned wb_ = (j < 2) ? cgb.x : cgb.y; const int sh = 16 * (j & 1);
;                 const float b0 = ((float)((wb_ >> sh) & 0xffu) - 128.f) * 0.03125f, b1 = ((float)((wb_ >> (sh + 8)) & 0xffu) - 128.f) * 0.03125f;
;                 gs[2 * j] = gwv[2 * j] * x0 * __builtin_amdgcn_rcpf((1.0f + __builtin_amdgcn_exp2f(-1.4426950408889634f * x0)) * (1.0f + __builtin_amdgcn_exp2f(-1.4426950408889634f * b0)));
;                 gs[2 * j + 1] = gwv[2 * j + 1] * x1 * __builtin_amdgcn_rcpf((1.0f + __builtin_amdgcn_exp2f(-1.4426950408889634f * x1)) * (1.0f + __builtin_amdgcn_exp2f(-1.4426950408889634f * b1))); }
;     ...
;             __syncthreads();
;             GLA_TICK(7);
;             if (c + 1 < SEQ / GCHUNK) GLA_STORE();
;             { const int row = tid >> 3, cg = tid & 7;
;                 const LAS f32x4* o0 = (const LAS f32x4*)(lds + L_OP + row * OST + cg * 32); const LAS f32x4* o1 = (const LAS f32x4*)(lds + L_OP + 64 * OST + row * OST + cg * 32);
;                 const f32x4 a = o0[0] + o1[0], bq = o0[1] + o1[1];
;                 v4u wv; wv.x = cvtpk(a[0] * gs[0], a[1] * gs[1]); wv.y = cvtpk(a[2] * gs[2], a[3] * gs[3]); wv.z = cvtpk(bq[0] * gs[4], bq[1] * gs[5]); wv.w = cvtpk(bq[2] * gs[6], bq[3] * gs[7]);
;                 const size_t grow = (size_t)c * GCHUNK + row;
;                 *(v4u*)(go0 + grow * gpitch + cg * 8) = wv;
;                 float ss = (a[0] * a[0] + a[1] * a[1]) + (a[2] * a[2] + a[3] * a[3]) + (bq[0] * bq[0] + bq[1] * bq[1]) + (bq[2] * bq[2] + bq[3] * bq[3]);
;                 ss += __shfl_xor(ss, 1); ss += __shfl_xor(ss, 2); ss += __shfl_xor(ss, 4);
;                 if (cg == 0) F.SSQG()[((size_t)b * SEQ + grow) * 32 + h * 8 + vs] = ss; }
	v_mfma_f32_16x16x32_bf16 v[62:65], v[230:233], v[90:93], v[62:65]
	s_waitcnt vmcnt(7)
	ds_write_b128 v172, v[190:193]
	s_waitcnt vmcnt(6)
	ds_write_b128 v173, v[194:197] offset:33792
	s_waitcnt vmcnt(5)
	ds_write_b128 v174, v[198:201]
	s_waitcnt vmcnt(4)
	ds_write_b128 v175, v[202:205] offset:33792
	s_waitcnt vmcnt(3)
	ds_write_b128 v172, v[206:209] offset:16896
	s_waitcnt vmcnt(2)
	ds_write_b128 v176, v[210:213] offset:33792
	s_waitcnt vmcnt(1)
	ds_write_b128 v177, v[214:217]
	s_waitcnt vmcnt(0)
	ds_write_b128 v178, v[218:221] offset:33792
	ds_write_b128 v179, v[50:53]
	ds_write_b128 v180, v[54:57]
	s_and_saveexec_b64 s[28:29], s[4:5]
	ds_write_b32 v129, v127
	s_or_b64 exec, exec, s[28:29]
	v_add_u32_sdwa v50, v158, s65 dst_sel:DWORD dst_unused:UNUSED_PAD src0_sel:BYTE_0 src1_sel:DWORD
	v_cvt_f32_i32_e32 v50, v50
	v_add_u32_sdwa v51, v158, s65 dst_sel:DWORD dst_unused:UNUSED_PAD src0_sel:BYTE_1 src1_sel:DWORD
	v_cvt_f32_i32_e32 v51, v51
	v_lshlrev_b32_e32 v52, 16, v14
	v_mul_f32_e32 v50, 0x3d000000, v50
	v_mul_f32_e32 v50, 0xbfb8aa3b, v50
	v_and_b32_e32 v53, 0xffff0000, v14
	v_mul_f32_e32 v14, 0xbfb8aa3b, v52
	v_mul_f32_e32 v55, 0x3d000000, v51
	v_exp_f32_e32 v51, v50
	v_exp_f32_e32 v50, v14
	v_mul_f32_e32 v14, 0xbfb8aa3b, v53
	v_exp_f32_e32 v54, v14
	v_mul_f32_e32 v14, 0xbfb8aa3b, v55
	v_pk_add_f32 v[50:51], v[50:51], 1.0 op_sel_hi:[1,0]
	v_exp_f32_e32 v55, v14
	v_mul_f32_e32 v14, v50, v51
	v_rcp_f32_e32 v50, v14
	v_add_u32_sdwa v14, v158, s65 dst_sel:DWORD dst_unused:UNUSED_PAD src0_sel:BYTE_2 src1_sel:DWORD
	v_cvt_f32_i32_e32 v14, v14
	v_add_u32_sdwa v51, v158, s65 dst_sel:DWORD dst_unused:UNUSED_PAD src0_sel:BYTE_3 src1_sel:DWORD
	v_cvt_f32_i32_e32 v56, v51
	v_pk_add_f32 v[54:55], v[54:55], 1.0 op_sel_hi:[1,0]
	v_mul_f32_e32 v14, 0x3d000000, v14
	v_mul_f32_e32 v14, 0xbfb8aa3b, v14
	v_mul_f32_e32 v51, v54, v55
	v_exp_f32_e32 v55, v14
	v_lshlrev_b32_e32 v14, 16, v15
	v_mul_f32_e32 v54, 0xbfb8aa3b, v14
	v_mul_f32_e32 v57, 0x3d000000, v56
	v_and_b32_e32 v15, 0xffff0000, v15
	v_exp_f32_e32 v54, v54
	v_mul_f32_e32 v56, 0xbfb8aa3b, v15
	v_mul_f32_e32 v57, 0xbfb8aa3b, v57
	v_exp_f32_e32 v56, v56
	v_exp_f32_e32 v57, v57
	v_pk_add_f32 v[54:55], v[54:55], 1.0 op_sel_hi:[1,0]
	v_lshlrev_b32_e32 v192, 16, v16
	v_mul_f32_e32 v54, v54, v55
	v_rcp_f32_e32 v190, v54
	v_pk_add_f32 v[54:55], v[56:57], 1.0 op_sel_hi:[1,0]
	v_add_u32_sdwa v56, v159, s65 dst_sel:DWORD dst_unused:UNUSED_PAD src0_sel:BYTE_0 src1_sel:DWORD
	v_cvt_f32_i32_e32 v56, v56
	v_add_u32_sdwa v57, v159, s65 dst_sel:DWORD dst_unused:UNUSED_PAD src0_sel:BYTE_1 src1_sel:DWORD
	v_mul_f32_e32 v54, v54, v55
	v_cvt_f32_i32_e32 v57, v57
	v_rcp_f32_e32 v191, v54
	v_mul_f32_e32 v54, 0x3d000000, v56
	v_mul_f32_e32 v54, 0xbfb8aa3b, v54
	v_and_b32_e32 v193, 0xffff0000, v16
	v_mul_f32_e32 v16, 0xbfb8aa3b, v192
	v_exp_f32_e32 v55, v54
	v_exp_f32_e32 v54, v16
	v_mul_f32_e32 v57, 0x3d000000, v57
	v_mul_f32_e32 v16, 0xbfb8aa3b, v193
	v_exp_f32_e32 v56, v16
	v_mul_f32_e32 v16, 0xbfb8aa3b, v57
	v_exp_f32_e32 v57, v16
	v_pk_add_f32 v[54:55], v[54:55], 1.0 op_sel_hi:[1,0]
	v_lshlrev_b32_e32 v194, 16, v17
	v_mul_f32_e32 v16, v54, v55
	v_rcp_f32_e32 v158, v16
	v_add_u32_sdwa v16, v159, s65 dst_sel:DWORD dst_unused:UNUSED_PAD src0_sel:BYTE_2 src1_sel:DWORD
	v_cvt_f32_i32_e32 v16, v16
	v_pk_add_f32 v[54:55], v[56:57], 1.0 op_sel_hi:[1,0]
	v_add_u32_sdwa v56, v159, s65 dst_sel:DWORD dst_unused:UNUSED_PAD src0_sel:BYTE_3 src1_sel:DWORD
	v_cvt_f32_i32_e32 v56, v56
	v_mul_f32_e32 v16, 0x3d000000, v16
	v_mul_f32_e32 v16, 0xbfb8aa3b, v16
	v_mul_f32_e32 v54, v54, v55
	v_mul_f32_e32 v56, 0x3d000000, v56
	v_exp_f32_e32 v55, v16
	v_and_b32_e32 v195, 0xffff0000, v17
	v_mul_f32_e32 v16, 0xbfb8aa3b, v194
	v_rcp_f32_e32 v159, v54
	v_exp_f32_e32 v54, v16
	v_mul_f32_e32 v16, 0xbfb8aa3b, v195
	v_mul_f32_e32 v17, 0xbfb8aa3b, v56
	v_exp_f32_e32 v16, v16
	v_exp_f32_e32 v17, v17
	v_rcp_f32_e32 v51, v51
	v_pk_add_f32 v[54:55], v[54:55], 1.0 op_sel_hi:[1,0]
	v_pk_mul_f32 v[200:201], v[8:9], v[14:15]
	v_pk_add_f32 v[16:17], v[16:17], 1.0 op_sel_hi:[1,0]
	v_mul_f32_e32 v54, v54, v55
	v_mul_f32_e32 v16, v16, v17
	v_rcp_f32_e32 v197, v16
	v_pk_mul_f32 v[16:17], v[6:7], v[52:53]
	v_rcp_f32_e32 v196, v54
	v_pk_mul_f32 v[198:199], v[16:17], v[50:51]
	ds_read_b128 v[14:17], v187
	ds_read_b128 v[50:53], v186
	ds_read_b128 v[54:57], v186 offset:16
	ds_read_b128 v[90:93], v187 offset:16
	v_pk_mul_f32 v[190:191], v[200:201], v[190:191]
	v_pk_mul_f32 v[192:193], v[2:3], v[192:193]
	s_waitcnt lgkmcnt(2)
	v_pk_add_f32 v[16:17], v[52:53], v[16:17]
	v_pk_add_f32 v[14:15], v[50:51], v[14:15]
	v_mul_f32_e32 v51, v17, v17
	v_mul_f32_e32 v50, v15, v15
	s_waitcnt lgkmcnt(0)
	v_pk_add_f32 v[52:53], v[54:55], v[90:91]
	v_fmac_f32_e32 v50, v14, v14
	v_fmac_f32_e32 v51, v16, v16
	v_add_f32_e32 v50, v50, v51
	v_mul_f32_e32 v51, v53, v53
	v_pk_add_f32 v[56:57], v[56:57], v[92:93]
	v_fmac_f32_e32 v51, v52, v52
	v_add_f32_e32 v50, v50, v51
	v_mul_f32_e32 v51, v57, v57
	v_fmac_f32_e32 v51, v56, v56
	v_add_f32_e32 v92, v51, v50
	ds_bpermute_b32 v93, v109, v92
	v_pk_mul_f32 v[50:51], v[4:5], v[194:195]
	v_pk_mul_f32 v[14:15], v[198:199], v[14:15]
	v_pk_mul_f32 v[90:91], v[50:51], v[196:197]
	v_cvt_pk_bf16_f32 v50, v14, v15
	s_waitcnt lgkmcnt(0)
	v_add_f32_e32 v92, v92, v93
	ds_bpermute_b32 v93, v160, v92
	v_pk_mul_f32 v[14:15], v[190:191], v[16:17]
	v_pk_mul_f32 v[54:55], v[192:193], v[158:159]
	v_cvt_pk_bf16_f32 v51, v14, v15
	v_pk_mul_f32 v[16:17], v[54:55], v[52:53]
	s_waitcnt lgkmcnt(0)
	v_add_f32_e32 v14, v92, v93
	ds_bpermute_b32 v15, v161, v14
	v_cvt_pk_bf16_f32 v52, v16, v17
	v_pk_mul_f32 v[16:17], v[90:91], v[56:57]
	s_nop 0
	v_cvt_pk_bf16_f32 v53, v16, v17
	global_store_dwordx4 v[142:143], v[50:53], off
	s_and_saveexec_b64 s[28:29], s[8:9]
	s_cbranch_execz .LBB0_553
	s_waitcnt lgkmcnt(0)
	v_add_f32_e32 v16, v14, v15
	v_lshl_add_u64 v[14:15], s[56:57], 0, v[144:145]
	global_store_dword v[14:15], v16, off
